# hand-written P0: pipelined 16KB units, wide loads, LDS-swizzled transpose
# speedup vs baseline: 1.0034x; 1.0034x over previous
; __device__ __forceinline__ unsigned pk2(float lo, float hi) { return f2bf(lo) | (f2bf(hi) << 16); }
; __global__ void __launch_bounds__(512, 2) fwd_megakernel(Args a) {
;     ...
;         for (int it = gw; it < I1 + I2 + I3 + I4 + I5; it += NGW) {
;             int r = it;
;             if (r < I1) { const int kb = r / 320, nb = r % 320; transpose_item(w_in_ab, 10240, 64 * kb, 32 * nb, WT1, 2048, 32 * nb, scr, lane); continue; } r -= I1;
;             if (r < I2) { const int kb = r / 64, nb = r % 64; transpose_item(w_out_ab, 2048, 64 * kb, 32 * nb, WT2, 3072, 32 * nb, scr, lane); continue; } r -= I2;
;             if (r < I3) { const int kb = r / 256, nb = r % 256; const int n0 = 32 * nb, part = n0 >> 11, chn = n0 & 2047;
;                 const int type = (part == 0 || part == 3) ? 1 : 0, bj = (part >= 2) ? 1 : 0;
;                 const int drow = 256 * (2 * (chn >> 7) + type) + 128 * bj + (chn & 127);
;                 transpose_item(w_in_c, 8192, 64 * kb, n0, WT3, 2048, drow, scr, lane); continue; } r -= I3;
;             if (r < I4) { const int kb = r / 64, nb = r % 64; transpose_item(w_out_c, 2048, 64 * kb, 32 * nb, WT4, 2048, 32 * nb, scr, lane); continue; } r -= I4;
;             { const int gi = r >> 5, rr = r & 31, kb = rr >> 3, nb = rr & 7; transpose_item(pool_w + (size_t)gi * 65536, 256, 64 * kb, 32 * nb, WT5, 256, gi * 256 + 32 * nb, scr, lane); }
;         }
;         for (size_t i = gt; i < (size_t)MT * DM / 8; i += (size_t)NGT * 4) {
;             f32x4 v0[4], v1[4];
; #pragma unroll
;             for (int u = 0; u < 4; ++u) { const size_t ii = i + (size_t)u * NGT; if (ii < (size_t)MT * DM / 8) { const size_t e = ii * 8; const float* src = e < (size_t)MP * DM ? x_prompt + e : x_sample + (e - (size_t)MP * DM);
;                 v0[u] = *(const f32x4*)src; v1[u] = *(const f32x4*)(src + 4); } }
; #pragma unroll
;             for (int u = 0; u < 4; ++u) { const size_t ii = i + (size_t)u * NGT; if (ii < (size_t)MT * DM / 8) { const size_t e = ii * 8;
;                 u32x4 o; o.x = pk2(v0[u][0], v0[u][1]); o.y = pk2(v0[u][2], v0[u][3]); o.z = pk2(v1[u][0], v1[u][1]); o.w = pk2(v1[u][2], v1[u][3]);
;                 *(u32x4*)(XB + e) = o; } } }
.LBB0_3:
	s_or_b64 exec, exec, s[2:3]
	s_load_dwordx16 s[44:59], s[0:1], 0x0
	s_lshr_b32 s0, s14, 6
	s_add_u32 s2, s92, 0x6000000
	s_addc_u32 s3, s93, 0
	s_add_u32 s4, s92, 0x8800000
	s_addc_u32 s5, s93, 0
	v_writelane_b32 v255, s4, 14
	v_lshlrev_b32_e32 v201, 3, v168
	s_waitcnt lgkmcnt(0)
	v_writelane_b32 v255, s5, 15
	s_add_u32 s4, s92, 0x9400000
	s_addc_u32 s5, s93, 0
	v_writelane_b32 v255, s4, 16
	s_barrier
	s_nop 0
	v_writelane_b32 v255, s5, 17
	s_add_u32 s4, s92, 0xb400000
	s_addc_u32 s5, s93, 0
	v_writelane_b32 v255, s4, 18
	s_add_u32 s8, s92, 0xbc00000
	s_addc_u32 s9, s93, 0
	v_writelane_b32 v255, s5, 19
	s_nop 0
	v_readlane_b32 s1, v255, 13
	s_lshl_b32 s1, s1, 3
	s_add_i32 s6, s0, s1
	v_writelane_b32 v255, s1, 20
	s_nop 0
	v_readlane_b32 s4, v255, 9
	v_readlane_b32 s5, v255, 10
	s_lshl_b32 s4, s4, 3
	v_writelane_b32 v255, s4, 21
	s_cmpk_gt_i32 s6, 0x5c7f
	s_nop 0
	v_writelane_b32 v255, s5, 22
	s_mov_b32 s4, s6
	v_writelane_b32 v255, s4, 23
	s_nop 1
	v_writelane_b32 v255, s5, 24
	v_readlane_b32 s60, v255, 23
	v_readlane_b32 s61, v255, 21
	v_readlane_b32 s82, v255, 2
	v_readlane_b32 s83, v255, 3
	v_readlane_b32 s84, v255, 14
	v_readlane_b32 s85, v255, 15
	v_readlane_b32 s86, v255, 16
	v_readlane_b32 s87, v255, 17
	v_readlane_b32 s88, v255, 18
	v_readlane_b32 s89, v255, 19
	v_and_b32_e32 v1, 63, v168
	v_readfirstlane_b32 s90, v168
	v_and_b32_e32 v252, 15, v1
	v_lshlrev_b32_e32 v2, 4, v252
	v_lshrrev_b32_e32 v253, 4, v1
	v_lshlrev_b32_e32 v68, 4, v253
	v_lshrrev_b32_e32 v69, 3, v1
	v_and_b32_e32 v254, 7, v1
	v_lshlrev_b32_e32 v128, 4, v254
	v_lshlrev_b32_e32 v170, 5, v1
	v_lshlrev_b32_e32 v171, 4, v1
	s_lshr_b32 s90, s90, 6
	s_lshl_b32 s90, s90, 13
	v_lshlrev_b32_e32 v180, 1, v253
	v_and_b32_e32 v181, 7, v252
	v_xor_b32_e32 v180, v180, v181
	v_lshlrev_b32_e32 v180, 4, v180
	v_lshl_add_u32 v180, v252, 9, v180
	v_add_u32_e32 v180, s90, v180
	v_xor_b32_e32 v181, 16, v180
	v_lshrrev_b32_e32 v252, 5, v1
	v_xor_b32_e32 v252, v254, v252
	v_lshlrev_b32_e32 v252, 4, v252
	v_lshl_add_u32 v252, v69, 7, v252
	v_add_u32_e32 v182, s90, v252
	v_xor_b32_e32 v200, 32, v182
	v_xor_b32_e32 v202, 64, v182
	v_xor_b32_e32 v203, 0x60, v182
	s_cmp_lt_u32 s60, 24128
	s_cbranch_scc0 .Lp0_done
	s_mov_b32 s62, s60
	s_cmp_lt_u32 s62, 11840
	s_cbranch_scc0 .Lp0_dx_a0
	s_mov_b32 s75, 1
	s_cmp_lt_u32 s62, 5120
	s_cbranch_scc0 .Lp0_d2_a0
	s_lshr_b32 s28, s62, 5
	s_mul_hi_u32 s29, s28, 0xcccccccd
	s_lshr_b32 s29, s29, 2
	s_mul_i32 s30, s29, 160
	s_sub_u32 s30, s62, s30
	s_mul_i32 s31, s29, 2621440
	s_lshl_b32 s32, s30, 8
	s_add_u32 s31, s31, s32
	s_add_u32 s64, s50, s31
	s_addc_u32 s65, s51, 0
	s_mov_b32 s66, 40960
	s_mul_i32 s31, s30, 262144
	s_lshl_b32 s32, s29, 7
	s_add_u32 s31, s31, s32
	s_add_u32 s72, s2, s31
	s_addc_u32 s73, s3, 0
	s_movk_i32 s74, 0x1000
	s_branch .Lp0_dd_a0
.Lp0_d2_a0:
	s_cmp_lt_u32 s62, 6656
	s_cbranch_scc0 .Lp0_d3_a0
	s_sub_u32 s28, s62, 5120
	s_lshr_b32 s29, s28, 5
	s_and_b32 s30, s28, 31
	s_mul_i32 s31, s29, 524288
	s_lshl_b32 s32, s30, 8
	s_add_u32 s31, s31, s32
	s_add_u32 s64, s56, s31
	s_addc_u32 s65, s57, 0
	s_movk_i32 s66, 0x2000
	s_mul_i32 s31, s30, 393216
	s_lshl_b32 s32, s29, 7
	s_add_u32 s31, s31, s32
	s_add_u32 s72, s84, s31
	s_addc_u32 s73, s85, 0
	s_movk_i32 s74, 0x1800
	s_branch .Lp0_dd_a0
.Lp0_d3_a0:
	s_cmp_lt_u32 s62, 10752
	s_cbranch_scc0 .Lp0_d4_a0
	s_sub_u32 s28, s62, 6656
	s_lshr_b32 s29, s28, 7
	s_and_b32 s30, s28, 127
	s_mul_i32 s31, s29, 2097152
	s_lshl_b32 s32, s30, 8
	s_add_u32 s31, s31, s32
	s_add_u32 s64, s58, s31
	s_addc_u32 s65, s59, 0
	s_mov_b32 s66, 0x8000
	s_lshr_b32 s33, s30, 5
	s_and_b32 s34, s30, 31
	s_lshr_b32 s34, s34, 1
	s_lshl_b32 s34, s34, 1
	s_cmp_eq_u32 s33, 0
	s_cselect_b32 s35, 1, 0
	s_cmp_eq_u32 s33, 3
	s_cselect_b32 s35, 1, s35
	s_add_u32 s34, s34, s35
	s_lshl_b32 s34, s34, 8
	s_cmp_ge_u32 s33, 2
	s_cselect_b32 s35, 128, 0
	s_add_u32 s34, s34, s35
	s_and_b32 s35, s30, 1
	s_lshl_b32 s35, s35, 6
	s_add_u32 s34, s34, s35
	s_lshl_b32 s31, s34, 12
	s_lshl_b32 s32, s29, 7
	s_add_u32 s31, s31, s32
	s_add_u32 s72, s86, s31
	s_addc_u32 s73, s87, 0
	s_movk_i32 s74, 0x1000
	s_branch .Lp0_dd_a0
.Lp0_d4_a0:
	s_cmp_lt_u32 s62, 11776
	s_cbranch_scc0 .Lp0_d5_a0
	s_sub_u32 s28, s62, 10752
	s_lshr_b32 s29, s28, 5
	s_and_b32 s30, s28, 31
	s_mul_i32 s31, s29, 524288
	s_lshl_b32 s32, s30, 8
	s_add_u32 s31, s31, s32
	s_add_u32 s64, s82, s31
	s_addc_u32 s65, s83, 0
	s_movk_i32 s66, 0x2000
	s_mul_i32 s31, s30, 262144
	s_lshl_b32 s32, s29, 7
	s_add_u32 s31, s31, s32
	s_add_u32 s72, s88, s31
	s_addc_u32 s73, s89, 0
	s_movk_i32 s74, 0x1000
	s_branch .Lp0_dd_a0
.Lp0_d5_a0:
	s_sub_u32 s28, s62, 11776
	s_lshr_b32 s33, s28, 4
	s_bfe_u32 s29, s28, 0x20002
	s_and_b32 s30, s28, 3
	s_lshl_b32 s31, s33, 18
	s_lshl_b32 s32, s29, 16
	s_add_u32 s31, s31, s32
	s_lshl_b32 s32, s30, 8
	s_add_u32 s31, s31, s32
	s_add_u32 s64, s52, s31
	s_addc_u32 s65, s53, 0
	s_movk_i32 s66, 0x400
	s_lshl_b32 s31, s33, 17
	s_lshl_b32 s32, s30, 15
	s_add_u32 s31, s31, s32
	s_lshl_b32 s32, s29, 7
	s_add_u32 s31, s31, s32
	s_add_u32 s72, s8, s31
	s_addc_u32 s73, s9, 0
	s_movk_i32 s74, 0x200
	s_branch .Lp0_dd_a0
.Lp0_dx_a0:
	s_mov_b32 s75, 0
	s_sub_u32 s28, s62, 11840
	s_lshl_b32 s31, s28, 13
	s_add_u32 s72, s92, s31
	s_addc_u32 s73, s93, 0
	s_cmp_lt_u32 s28, 4096
	s_cbranch_scc0 .Lp0_dx2_a0
	s_lshl_b32 s31, s28, 14
	s_add_u32 s64, s44, s31
	s_addc_u32 s65, s45, 0
	s_branch .Lp0_dd_a0
.Lp0_dx2_a0:
	s_sub_u32 s28, s28, 4096
	s_lshl_b32 s31, s28, 14
	s_add_u32 s64, s46, s31
	s_addc_u32 s65, s47, 0
; __global__ void __launch_bounds__(512, 2) fwd_megakernel(Args a) {
;     ...
;         for (int it = gw; it < I1 + I2 + I3 + I4 + I5; it += NGW) {
;             int r = it;
;             if (r < I1) { const int kb = r / 320, nb = r % 320; transpose_item(w_in_ab, 10240, 64 * kb, 32 * nb, WT1, 2048, 32 * nb, scr, lane); continue; } r -= I1;
;             if (r < I2) { const int kb = r / 64, nb = r % 64; transpose_item(w_out_ab, 2048, 64 * kb, 32 * nb, WT2, 3072, 32 * nb, scr, lane); continue; } r -= I2;
;             if (r < I3) { const int kb = r / 256, nb = r % 256; const int n0 = 32 * nb, part = n0 >> 11, chn = n0 & 2047;
;                 const int type = (part == 0 || part == 3) ? 1 : 0, bj = (part >= 2) ? 1 : 0;
;                 const int drow = 256 * (2 * (chn >> 7) + type) + 128 * bj + (chn & 127);
;                 transpose_item(w_in_c, 8192, 64 * kb, n0, WT3, 2048, drow, scr, lane); continue; } r -= I3;
;             if (r < I4) { const int kb = r / 64, nb = r % 64; transpose_item(w_out_c, 2048, 64 * kb, 32 * nb, WT4, 2048, 32 * nb, scr, lane); continue; } r -= I4;
;             { const int gi = r >> 5, rr = r & 31, kb = rr >> 3, nb = rr & 7; transpose_item(pool_w + (size_t)gi * 65536, 256, 64 * kb, 32 * nb, WT5, 256, gi * 256 + 32 * nb, scr, lane); }
;         }
;         for (size_t i = gt; i < (size_t)MT * DM / 8; i += (size_t)NGT * 4) {
;             f32x4 v0[4], v1[4];
; #pragma unroll
;             for (int u = 0; u < 4; ++u) { const size_t ii = i + (size_t)u * NGT; if (ii < (size_t)MT * DM / 8) { const size_t e = ii * 8; const float* src = e < (size_t)MP * DM ? x_prompt + e : x_sample + (e - (size_t)MP * DM);
;                 v0[u] = *(const f32x4*)src; v1[u] = *(const f32x4*)(src + 4); } }
.Lp0_dd_a0:
	s_cmp_eq_u32 s75, 0
	s_cbranch_scc1 .Lp0_lx_a0
	v_mad_u32_u24 v130, v68, s66, v2
	global_load_dwordx4 v[80:83], v130, s[64:65]
	s_add_u32 s64, s64, s66
	s_addc_u32 s65, s65, 0
	global_load_dwordx4 v[84:87], v130, s[64:65]
	s_add_u32 s64, s64, s66
	s_addc_u32 s65, s65, 0
	global_load_dwordx4 v[92:95], v130, s[64:65]
	s_add_u32 s64, s64, s66
	s_addc_u32 s65, s65, 0
	global_load_dwordx4 v[96:99], v130, s[64:65]
	s_add_u32 s64, s64, s66
	s_addc_u32 s65, s65, 0
	global_load_dwordx4 v[100:103], v130, s[64:65]
	s_add_u32 s64, s64, s66
	s_addc_u32 s65, s65, 0
	global_load_dwordx4 v[104:107], v130, s[64:65]
	s_add_u32 s64, s64, s66
	s_addc_u32 s65, s65, 0
	global_load_dwordx4 v[108:111], v130, s[64:65]
	s_add_u32 s64, s64, s66
	s_addc_u32 s65, s65, 0
	global_load_dwordx4 v[112:115], v130, s[64:65]
	s_add_u32 s64, s64, s66
	s_addc_u32 s65, s65, 0
	global_load_dwordx4 v[116:119], v130, s[64:65]
	s_add_u32 s64, s64, s66
	s_addc_u32 s65, s65, 0
	global_load_dwordx4 v[136:139], v130, s[64:65]
	s_add_u32 s64, s64, s66
	s_addc_u32 s65, s65, 0
	global_load_dwordx4 v[140:143], v130, s[64:65]
	s_add_u32 s64, s64, s66
	s_addc_u32 s65, s65, 0
	global_load_dwordx4 v[144:147], v130, s[64:65]
	s_add_u32 s64, s64, s66
	s_addc_u32 s65, s65, 0
	global_load_dwordx4 v[148:151], v130, s[64:65]
	s_add_u32 s64, s64, s66
	s_addc_u32 s65, s65, 0
	global_load_dwordx4 v[152:155], v130, s[64:65]
	s_add_u32 s64, s64, s66
	s_addc_u32 s65, s65, 0
	global_load_dwordx4 v[156:159], v130, s[64:65]
	s_add_u32 s64, s64, s66
	s_addc_u32 s65, s65, 0
	global_load_dwordx4 v[160:163], v130, s[64:65]
	s_branch .Lp0_le_a0
.Lp0_lx_a0:
	global_load_dwordx4 v[80:83], v170, s[64:65] offset:0
	global_load_dwordx4 v[84:87], v170, s[64:65] offset:16
	global_load_dwordx4 v[92:95], v170, s[64:65] offset:2048
	global_load_dwordx4 v[96:99], v170, s[64:65] offset:2064
	s_add_u32 s64, s64, 0x1000
	s_addc_u32 s65, s65, 0
	global_load_dwordx4 v[100:103], v170, s[64:65] offset:0
	global_load_dwordx4 v[104:107], v170, s[64:65] offset:16
	global_load_dwordx4 v[108:111], v170, s[64:65] offset:2048
	global_load_dwordx4 v[112:115], v170, s[64:65] offset:2064
	s_add_u32 s64, s64, 0x1000
	s_addc_u32 s65, s65, 0
	global_load_dwordx4 v[116:119], v170, s[64:65] offset:0
	global_load_dwordx4 v[136:139], v170, s[64:65] offset:16
	global_load_dwordx4 v[140:143], v170, s[64:65] offset:2048
	global_load_dwordx4 v[144:147], v170, s[64:65] offset:2064
	s_add_u32 s64, s64, 0x1000
	s_addc_u32 s65, s65, 0
	global_load_dwordx4 v[148:151], v170, s[64:65] offset:0
	global_load_dwordx4 v[152:155], v170, s[64:65] offset:16
	global_load_dwordx4 v[156:159], v170, s[64:65] offset:2048
	global_load_dwordx4 v[160:163], v170, s[64:65] offset:2064
.Lp0_le_a0:
.Lp0_loop:
	s_add_u32 s60, s60, s61
	s_cmp_lt_u32 s60, 24128
	s_cbranch_scc0 .Lp0_nob
	s_mov_b32 s62, s60
	s_cmp_lt_u32 s62, 11840
	s_cbranch_scc0 .Lp0_dx_b
	s_mov_b32 s79, 1
	s_cmp_lt_u32 s62, 5120
	s_cbranch_scc0 .Lp0_d2_b
	s_lshr_b32 s28, s62, 5
	s_mul_hi_u32 s29, s28, 0xcccccccd
	s_lshr_b32 s29, s29, 2
	s_mul_i32 s30, s29, 160
	s_sub_u32 s30, s62, s30
	s_mul_i32 s31, s29, 2621440
	s_lshl_b32 s32, s30, 8
	s_add_u32 s31, s31, s32
	s_add_u32 s64, s50, s31
	s_addc_u32 s65, s51, 0
	s_mov_b32 s66, 40960
	s_mul_i32 s31, s30, 262144
	s_lshl_b32 s32, s29, 7
	s_add_u32 s31, s31, s32
	s_add_u32 s76, s2, s31
	s_addc_u32 s77, s3, 0
	s_movk_i32 s78, 0x1000
	s_branch .Lp0_dd_b
.Lp0_d2_b:
	s_cmp_lt_u32 s62, 6656
	s_cbranch_scc0 .Lp0_d3_b
	s_sub_u32 s28, s62, 5120
	s_lshr_b32 s29, s28, 5
	s_and_b32 s30, s28, 31
	s_mul_i32 s31, s29, 524288
	s_lshl_b32 s32, s30, 8
	s_add_u32 s31, s31, s32
	s_add_u32 s64, s56, s31
	s_addc_u32 s65, s57, 0
	s_movk_i32 s66, 0x2000
	s_mul_i32 s31, s30, 393216
	s_lshl_b32 s32, s29, 7
	s_add_u32 s31, s31, s32
	s_add_u32 s76, s84, s31
	s_addc_u32 s77, s85, 0
	s_movk_i32 s78, 0x1800
	s_branch .Lp0_dd_b
.Lp0_d3_b:
	s_cmp_lt_u32 s62, 10752
	s_cbranch_scc0 .Lp0_d4_b
	s_sub_u32 s28, s62, 6656
	s_lshr_b32 s29, s28, 7
	s_and_b32 s30, s28, 127
	s_mul_i32 s31, s29, 2097152
	s_lshl_b32 s32, s30, 8
	s_add_u32 s31, s31, s32
	s_add_u32 s64, s58, s31
	s_addc_u32 s65, s59, 0
	s_mov_b32 s66, 0x8000
	s_lshr_b32 s33, s30, 5
	s_and_b32 s34, s30, 31
	s_lshr_b32 s34, s34, 1
	s_lshl_b32 s34, s34, 1
	s_cmp_eq_u32 s33, 0
	s_cselect_b32 s35, 1, 0
	s_cmp_eq_u32 s33, 3
	s_cselect_b32 s35, 1, s35
	s_add_u32 s34, s34, s35
	s_lshl_b32 s34, s34, 8
	s_cmp_ge_u32 s33, 2
	s_cselect_b32 s35, 128, 0
	s_add_u32 s34, s34, s35
	s_and_b32 s35, s30, 1
	s_lshl_b32 s35, s35, 6
	s_add_u32 s34, s34, s35
	s_lshl_b32 s31, s34, 12
	s_lshl_b32 s32, s29, 7
	s_add_u32 s31, s31, s32
	s_add_u32 s76, s86, s31
	s_addc_u32 s77, s87, 0
	s_movk_i32 s78, 0x1000
	s_branch .Lp0_dd_b
.Lp0_d4_b:
	s_cmp_lt_u32 s62, 11776
	s_cbranch_scc0 .Lp0_d5_b
	s_sub_u32 s28, s62, 10752
	s_lshr_b32 s29, s28, 5
	s_and_b32 s30, s28, 31
	s_mul_i32 s31, s29, 524288
	s_lshl_b32 s32, s30, 8
	s_add_u32 s31, s31, s32
	s_add_u32 s64, s82, s31
	s_addc_u32 s65, s83, 0
	s_movk_i32 s66, 0x2000
	s_mul_i32 s31, s30, 262144
	s_lshl_b32 s32, s29, 7
	s_add_u32 s31, s31, s32
	s_add_u32 s76, s88, s31
	s_addc_u32 s77, s89, 0
	s_movk_i32 s78, 0x1000
	s_branch .Lp0_dd_b
.Lp0_d5_b:
	s_sub_u32 s28, s62, 11776
	s_lshr_b32 s33, s28, 4
	s_bfe_u32 s29, s28, 0x20002
	s_and_b32 s30, s28, 3
	s_lshl_b32 s31, s33, 18
	s_lshl_b32 s32, s29, 16
	s_add_u32 s31, s31, s32
	s_lshl_b32 s32, s30, 8
	s_add_u32 s31, s31, s32
	s_add_u32 s64, s52, s31
	s_addc_u32 s65, s53, 0
	s_movk_i32 s66, 0x400
	s_lshl_b32 s31, s33, 17
	s_lshl_b32 s32, s30, 15
	s_add_u32 s31, s31, s32
	s_lshl_b32 s32, s29, 7
	s_add_u32 s31, s31, s32
	s_add_u32 s76, s8, s31
	s_addc_u32 s77, s9, 0
	s_movk_i32 s78, 0x200
	s_branch .Lp0_dd_b
.Lp0_dx_b:
	s_mov_b32 s79, 0
	s_sub_u32 s28, s62, 11840
	s_lshl_b32 s31, s28, 13
	s_add_u32 s76, s92, s31
	s_addc_u32 s77, s93, 0
	s_cmp_lt_u32 s28, 4096
	s_cbranch_scc0 .Lp0_dx2_b
	s_lshl_b32 s31, s28, 14
	s_add_u32 s64, s44, s31
	s_addc_u32 s65, s45, 0
	s_branch .Lp0_dd_b

; __global__ void __launch_bounds__(512, 2) fwd_megakernel(Args a) {
;     ...
;         for (int it = gw; it < I1 + I2 + I3 + I4 + I5; it += NGW) {
;             int r = it;
;             if (r < I1) { const int kb = r / 320, nb = r % 320; transpose_item(w_in_ab, 10240, 64 * kb, 32 * nb, WT1, 2048, 32 * nb, scr, lane); continue; } r -= I1;
;             if (r < I2) { const int kb = r / 64, nb = r % 64; transpose_item(w_out_ab, 2048, 64 * kb, 32 * nb, WT2, 3072, 32 * nb, scr, lane); continue; } r -= I2;
;             if (r < I3) { const int kb = r / 256, nb = r % 256; const int n0 = 32 * nb, part = n0 >> 11, chn = n0 & 2047;
;                 const int type = (part == 0 || part == 3) ? 1 : 0, bj = (part >= 2) ? 1 : 0;
;                 const int drow = 256 * (2 * (chn >> 7) + type) + 128 * bj + (chn & 127);
;                 transpose_item(w_in_c, 8192, 64 * kb, n0, WT3, 2048, drow, scr, lane); continue; } r -= I3;
;             if (r < I4) { const int kb = r / 64, nb = r % 64; transpose_item(w_out_c, 2048, 64 * kb, 32 * nb, WT4, 2048, 32 * nb, scr, lane); continue; } r -= I4;
;             { const int gi = r >> 5, rr = r & 31, kb = rr >> 3, nb = rr & 7; transpose_item(pool_w + (size_t)gi * 65536, 256, 64 * kb, 32 * nb, WT5, 256, gi * 256 + 32 * nb, scr, lane); }
;         }
;         for (size_t i = gt; i < (size_t)MT * DM / 8; i += (size_t)NGT * 4) {
;             f32x4 v0[4], v1[4];
; #pragma unroll
;             for (int u = 0; u < 4; ++u) { const size_t ii = i + (size_t)u * NGT; if (ii < (size_t)MT * DM / 8) { const size_t e = ii * 8; const float* src = e < (size_t)MP * DM ? x_prompt + e : x_sample + (e - (size_t)MP * DM);
;                 v0[u] = *(const f32x4*)src; v1[u] = *(const f32x4*)(src + 4); } }
.Lp0_dd_b:
	s_cmp_eq_u32 s79, 0
	s_cbranch_scc1 .Lp0_lx_b
	v_mad_u32_u24 v130, v68, s66, v2
	global_load_dwordx4 v[184:187], v130, s[64:65]
	s_add_u32 s64, s64, s66
	s_addc_u32 s65, s65, 0
	global_load_dwordx4 v[188:191], v130, s[64:65]
	s_add_u32 s64, s64, s66
	s_addc_u32 s65, s65, 0
	global_load_dwordx4 v[192:195], v130, s[64:65]
	s_add_u32 s64, s64, s66
	s_addc_u32 s65, s65, 0
	global_load_dwordx4 v[196:199], v130, s[64:65]
	s_add_u32 s64, s64, s66
	s_addc_u32 s65, s65, 0
	global_load_dwordx4 v[204:207], v130, s[64:65]
	s_add_u32 s64, s64, s66
	s_addc_u32 s65, s65, 0
	global_load_dwordx4 v[208:211], v130, s[64:65]
	s_add_u32 s64, s64, s66
	s_addc_u32 s65, s65, 0
	global_load_dwordx4 v[212:215], v130, s[64:65]
	s_add_u32 s64, s64, s66
	s_addc_u32 s65, s65, 0
	global_load_dwordx4 v[216:219], v130, s[64:65]
	s_add_u32 s64, s64, s66
	s_addc_u32 s65, s65, 0
	global_load_dwordx4 v[220:223], v130, s[64:65]
	s_add_u32 s64, s64, s66
	s_addc_u32 s65, s65, 0
	global_load_dwordx4 v[224:227], v130, s[64:65]
	s_add_u32 s64, s64, s66
	s_addc_u32 s65, s65, 0
	global_load_dwordx4 v[228:231], v130, s[64:65]
	s_add_u32 s64, s64, s66
	s_addc_u32 s65, s65, 0
	global_load_dwordx4 v[232:235], v130, s[64:65]
	s_add_u32 s64, s64, s66
	s_addc_u32 s65, s65, 0
	global_load_dwordx4 v[236:239], v130, s[64:65]
	s_add_u32 s64, s64, s66
	s_addc_u32 s65, s65, 0
	global_load_dwordx4 v[240:243], v130, s[64:65]
	s_add_u32 s64, s64, s66
	s_addc_u32 s65, s65, 0
	global_load_dwordx4 v[244:247], v130, s[64:65]
	s_add_u32 s64, s64, s66
	s_addc_u32 s65, s65, 0
	global_load_dwordx4 v[248:251], v130, s[64:65]
	s_branch .Lp0_le_b
.Lp0_lx_b:
	global_load_dwordx4 v[184:187], v170, s[64:65] offset:0
	global_load_dwordx4 v[188:191], v170, s[64:65] offset:16
	global_load_dwordx4 v[192:195], v170, s[64:65] offset:2048
	global_load_dwordx4 v[196:199], v170, s[64:65] offset:2064
	s_add_u32 s64, s64, 0x1000
	s_addc_u32 s65, s65, 0
	global_load_dwordx4 v[204:207], v170, s[64:65] offset:0
	global_load_dwordx4 v[208:211], v170, s[64:65] offset:16
	global_load_dwordx4 v[212:215], v170, s[64:65] offset:2048
	global_load_dwordx4 v[216:219], v170, s[64:65] offset:2064
	s_add_u32 s64, s64, 0x1000
	s_addc_u32 s65, s65, 0
	global_load_dwordx4 v[220:223], v170, s[64:65] offset:0
	global_load_dwordx4 v[224:227], v170, s[64:65] offset:16
	global_load_dwordx4 v[228:231], v170, s[64:65] offset:2048
	global_load_dwordx4 v[232:235], v170, s[64:65] offset:2064
	s_add_u32 s64, s64, 0x1000
	s_addc_u32 s65, s65, 0
	global_load_dwordx4 v[236:239], v170, s[64:65] offset:0
	global_load_dwordx4 v[240:243], v170, s[64:65] offset:16
	global_load_dwordx4 v[244:247], v170, s[64:65] offset:2048
	global_load_dwordx4 v[248:251], v170, s[64:65] offset:2064
.Lp0_le_b:
	s_waitcnt vmcnt(16)
	s_branch .Lp0_pa

; #define LAS __attribute__((address_space(3)))
; __device__ __forceinline__ unsigned pk2(float lo, float hi) { return f2bf(lo) | (f2bf(hi) << 16); }
; __device__ __forceinline__ void transpose_item(const float* W, int N, int k0, int n0, bf16_t* WT, int ldt, int drow0, LAS float* scr, int lane) {
;     float wv[32];
; #pragma unroll
;     for (int i = 0; i < 32; ++i) { const int kk = 2 * i + (lane >> 5); wv[i] = W[(size_t)(k0 + kk) * N + n0 + (lane & 31)]; }
; #pragma unroll
;     for (int i = 0; i < 32; ++i) { const int kk = 2 * i + (lane >> 5); scr[kk * 33 + (lane & 31)] = wv[i]; }
;     asm volatile("s_waitcnt lgkmcnt(0)" ::: "memory");
;     const int c = lane & 7;
; #pragma unroll
;     for (int j = 0; j < 4; ++j) { const int n = (lane >> 3) + 8 * j; const LAS float* s = scr + (8 * c) * 33 + n;
;         u32x4 o; o.x = pk2(s[0 * 33], s[1 * 33]); o.y = pk2(s[2 * 33], s[3 * 33]); o.z = pk2(s[4 * 33], s[5 * 33]); o.w = pk2(s[6 * 33], s[7 * 33]);
;         *(u32x4*)(WT + (size_t)(drow0 + n) * ldt + k0 + 8 * c) = o; }
;     asm volatile("s_waitcnt lgkmcnt(0)" ::: "memory");
; }
; __global__ void __launch_bounds__(512, 2) fwd_megakernel(Args a) {
;     ...
;             for (int u = 0; u < 4; ++u) { const size_t ii = i + (size_t)u * NGT; if (ii < (size_t)MT * DM / 8) { const size_t e = ii * 8;
;                 u32x4 o; o.x = pk2(v0[u][0], v0[u][1]); o.y = pk2(v0[u][2], v0[u][3]); o.z = pk2(v1[u][0], v1[u][1]); o.w = pk2(v1[u][2], v1[u][3]);
;                 *(u32x4*)(XB + e) = o; } } }
.Lp0_pa:
	s_cmp_eq_u32 s75, 0
	s_cbranch_scc1 .Lp0_px_a
	v_cvt_pk_bf16_f32 v64, v80, v84
	v_cvt_pk_bf16_f32 v164, v81, v85
	v_cvt_pk_bf16_f32 v172, v82, v86
	v_cvt_pk_bf16_f32 v176, v83, v87
	v_cvt_pk_bf16_f32 v65, v92, v96
	v_cvt_pk_bf16_f32 v165, v93, v97
	v_cvt_pk_bf16_f32 v173, v94, v98
	v_cvt_pk_bf16_f32 v177, v95, v99
	v_cvt_pk_bf16_f32 v66, v100, v104
	v_cvt_pk_bf16_f32 v166, v101, v105
	v_cvt_pk_bf16_f32 v174, v102, v106
	v_cvt_pk_bf16_f32 v178, v103, v107
	v_cvt_pk_bf16_f32 v67, v108, v112
	v_cvt_pk_bf16_f32 v167, v109, v113
	v_cvt_pk_bf16_f32 v175, v110, v114
	v_cvt_pk_bf16_f32 v179, v111, v115
	ds_write_b128 v180, v[64:67] offset:0
	ds_write_b128 v180, v[164:167] offset:128
	ds_write_b128 v180, v[172:175] offset:256
	ds_write_b128 v180, v[176:179] offset:384
	v_cvt_pk_bf16_f32 v64, v116, v136
	v_cvt_pk_bf16_f32 v164, v117, v137
	v_cvt_pk_bf16_f32 v172, v118, v138
	v_cvt_pk_bf16_f32 v176, v119, v139
	v_cvt_pk_bf16_f32 v65, v140, v144
	v_cvt_pk_bf16_f32 v165, v141, v145
	v_cvt_pk_bf16_f32 v173, v142, v146
	v_cvt_pk_bf16_f32 v177, v143, v147
	v_cvt_pk_bf16_f32 v66, v148, v152
	v_cvt_pk_bf16_f32 v166, v149, v153
	v_cvt_pk_bf16_f32 v174, v150, v154
	v_cvt_pk_bf16_f32 v178, v151, v155
	v_cvt_pk_bf16_f32 v67, v156, v160
	v_cvt_pk_bf16_f32 v167, v157, v161
	v_cvt_pk_bf16_f32 v175, v158, v162
	v_cvt_pk_bf16_f32 v179, v159, v163
	ds_write_b128 v181, v[64:67] offset:0
	ds_write_b128 v181, v[164:167] offset:128
	ds_write_b128 v181, v[172:175] offset:256
	ds_write_b128 v181, v[176:179] offset:384
	v_mad_u32_u24 v169, v69, s74, v128
	s_lshl_b32 s28, s74, 3
	s_waitcnt lgkmcnt(0)
	ds_read_b128 v[80:83], v182 offset:0
	ds_read_b128 v[84:87], v200 offset:1024
	ds_read_b128 v[92:95], v202 offset:2048
	ds_read_b128 v[96:99], v203 offset:3072
	ds_read_b128 v[100:103], v182 offset:4096
	ds_read_b128 v[104:107], v200 offset:5120
	ds_read_b128 v[108:111], v202 offset:6144
	ds_read_b128 v[112:115], v203 offset:7168
	s_waitcnt lgkmcnt(7)
	global_store_dwordx4 v169, v[80:83], s[72:73]
	s_add_u32 s72, s72, s28
	s_addc_u32 s73, s73, 0
	s_waitcnt lgkmcnt(6)
	global_store_dwordx4 v169, v[84:87], s[72:73]
	s_add_u32 s72, s72, s28
	s_addc_u32 s73, s73, 0
	s_waitcnt lgkmcnt(5)
	global_store_dwordx4 v169, v[92:95], s[72:73]
	s_add_u32 s72, s72, s28
	s_addc_u32 s73, s73, 0
	s_waitcnt lgkmcnt(4)
	global_store_dwordx4 v169, v[96:99], s[72:73]
	s_add_u32 s72, s72, s28
	s_addc_u32 s73, s73, 0
	s_waitcnt lgkmcnt(3)
	global_store_dwordx4 v169, v[100:103], s[72:73]
	s_add_u32 s72, s72, s28
	s_addc_u32 s73, s73, 0
	s_waitcnt lgkmcnt(2)
	global_store_dwordx4 v169, v[104:107], s[72:73]
	s_add_u32 s72, s72, s28
	s_addc_u32 s73, s73, 0
	s_waitcnt lgkmcnt(1)
	global_store_dwordx4 v169, v[108:111], s[72:73]
	s_add_u32 s72, s72, s28
	s_addc_u32 s73, s73, 0
	s_waitcnt lgkmcnt(0)
	global_store_dwordx4 v169, v[112:115], s[72:73]
	s_branch .Lp0_pe_a
.Lp0_px_a:
	v_cvt_pk_bf16_f32 v80, v80, v81
	v_cvt_pk_bf16_f32 v81, v82, v83
	v_cvt_pk_bf16_f32 v82, v84, v85
	v_cvt_pk_bf16_f32 v83, v86, v87
	global_store_dwordx4 v171, v[80:83], s[72:73] offset:0
	v_cvt_pk_bf16_f32 v92, v92, v93
	v_cvt_pk_bf16_f32 v93, v94, v95
	v_cvt_pk_bf16_f32 v94, v96, v97
	v_cvt_pk_bf16_f32 v95, v98, v99
	global_store_dwordx4 v171, v[92:95], s[72:73] offset:1024
	v_cvt_pk_bf16_f32 v100, v100, v101
	v_cvt_pk_bf16_f32 v101, v102, v103
	v_cvt_pk_bf16_f32 v102, v104, v105
	v_cvt_pk_bf16_f32 v103, v106, v107
	global_store_dwordx4 v171, v[100:103], s[72:73] offset:2048
	v_cvt_pk_bf16_f32 v108, v108, v109
	v_cvt_pk_bf16_f32 v109, v110, v111
	v_cvt_pk_bf16_f32 v110, v112, v113
	v_cvt_pk_bf16_f32 v111, v114, v115
	global_store_dwordx4 v171, v[108:111], s[72:73] offset:3072
	s_add_u32 s72, s72, 0x1000
	s_addc_u32 s73, s73, 0
	v_cvt_pk_bf16_f32 v116, v116, v117
	v_cvt_pk_bf16_f32 v117, v118, v119
	v_cvt_pk_bf16_f32 v118, v136, v137
	v_cvt_pk_bf16_f32 v119, v138, v139
	global_store_dwordx4 v171, v[116:119], s[72:73] offset:0
	v_cvt_pk_bf16_f32 v140, v140, v141
	v_cvt_pk_bf16_f32 v141, v142, v143
	v_cvt_pk_bf16_f32 v142, v144, v145
	v_cvt_pk_bf16_f32 v143, v146, v147
	global_store_dwordx4 v171, v[140:143], s[72:73] offset:1024
	v_cvt_pk_bf16_f32 v148, v148, v149
	v_cvt_pk_bf16_f32 v149, v150, v151
	v_cvt_pk_bf16_f32 v150, v152, v153
	v_cvt_pk_bf16_f32 v151, v154, v155
	global_store_dwordx4 v171, v[148:151], s[72:73] offset:2048
	v_cvt_pk_bf16_f32 v156, v156, v157
	v_cvt_pk_bf16_f32 v157, v158, v159
	v_cvt_pk_bf16_f32 v158, v160, v161
	v_cvt_pk_bf16_f32 v159, v162, v163
	global_store_dwordx4 v171, v[156:159], s[72:73] offset:3072
.Lp0_pe_a:
	s_cmp_lt_u32 s60, 24128
	s_cbranch_scc0 .Lp0_done
	s_add_u32 s60, s60, s61
	s_cmp_lt_u32 s60, 24128
	s_cbranch_scc0 .Lp0_noa
	s_mov_b32 s62, s60
	s_cmp_lt_u32 s62, 11840
	s_cbranch_scc0 .Lp0_dx_a1
	s_mov_b32 s75, 1
	s_cmp_lt_u32 s62, 5120
	s_cbranch_scc0 .Lp0_d2_a1
	s_lshr_b32 s28, s62, 5
	s_mul_hi_u32 s29, s28, 0xcccccccd
	s_lshr_b32 s29, s29, 2
	s_mul_i32 s30, s29, 160
	s_sub_u32 s30, s62, s30
	s_mul_i32 s31, s29, 2621440
	s_lshl_b32 s32, s30, 8
	s_add_u32 s31, s31, s32
	s_add_u32 s64, s50, s31
	s_addc_u32 s65, s51, 0
	s_mov_b32 s66, 40960
	s_mul_i32 s31, s30, 262144
	s_lshl_b32 s32, s29, 7
	s_add_u32 s31, s31, s32
	s_add_u32 s72, s2, s31
	s_addc_u32 s73, s3, 0
	s_movk_i32 s74, 0x1000
	s_branch .Lp0_dd_a1

; #define LAS __attribute__((address_space(3)))
; __device__ __forceinline__ unsigned pk2(float lo, float hi) { return f2bf(lo) | (f2bf(hi) << 16); }
; __device__ __forceinline__ void transpose_item(const float* W, int N, int k0, int n0, bf16_t* WT, int ldt, int drow0, LAS float* scr, int lane) {
;     float wv[32];
; #pragma unroll
;     for (int i = 0; i < 32; ++i) { const int kk = 2 * i + (lane >> 5); wv[i] = W[(size_t)(k0 + kk) * N + n0 + (lane & 31)]; }
; #pragma unroll
;     for (int i = 0; i < 32; ++i) { const int kk = 2 * i + (lane >> 5); scr[kk * 33 + (lane & 31)] = wv[i]; }
;     asm volatile("s_waitcnt lgkmcnt(0)" ::: "memory");
;     const int c = lane & 7;
; #pragma unroll
;     for (int j = 0; j < 4; ++j) { const int n = (lane >> 3) + 8 * j; const LAS float* s = scr + (8 * c) * 33 + n;
;         u32x4 o; o.x = pk2(s[0 * 33], s[1 * 33]); o.y = pk2(s[2 * 33], s[3 * 33]); o.z = pk2(s[4 * 33], s[5 * 33]); o.w = pk2(s[6 * 33], s[7 * 33]);
;         *(u32x4*)(WT + (size_t)(drow0 + n) * ldt + k0 + 8 * c) = o; }
;     asm volatile("s_waitcnt lgkmcnt(0)" ::: "memory");
; }
; __global__ void __launch_bounds__(512, 2) fwd_megakernel(Args a) {
;     ...
;             for (int u = 0; u < 4; ++u) { const size_t ii = i + (size_t)u * NGT; if (ii < (size_t)MT * DM / 8) { const size_t e = ii * 8;
;                 u32x4 o; o.x = pk2(v0[u][0], v0[u][1]); o.y = pk2(v0[u][2], v0[u][3]); o.z = pk2(v1[u][0], v1[u][1]); o.w = pk2(v1[u][2], v1[u][3]);
;                 *(u32x4*)(XB + e) = o; } } }
.Lp0_pb:
	s_cmp_eq_u32 s79, 0
	s_cbranch_scc1 .Lp0_px_b
	v_cvt_pk_bf16_f32 v64, v184, v188
	v_cvt_pk_bf16_f32 v164, v185, v189
	v_cvt_pk_bf16_f32 v172, v186, v190
	v_cvt_pk_bf16_f32 v176, v187, v191
	v_cvt_pk_bf16_f32 v65, v192, v196
	v_cvt_pk_bf16_f32 v165, v193, v197
	v_cvt_pk_bf16_f32 v173, v194, v198
	v_cvt_pk_bf16_f32 v177, v195, v199
	v_cvt_pk_bf16_f32 v66, v204, v208
	v_cvt_pk_bf16_f32 v166, v205, v209
	v_cvt_pk_bf16_f32 v174, v206, v210
	v_cvt_pk_bf16_f32 v178, v207, v211
	v_cvt_pk_bf16_f32 v67, v212, v216
	v_cvt_pk_bf16_f32 v167, v213, v217
	v_cvt_pk_bf16_f32 v175, v214, v218
	v_cvt_pk_bf16_f32 v179, v215, v219
	ds_write_b128 v180, v[64:67] offset:0
	ds_write_b128 v180, v[164:167] offset:128
	ds_write_b128 v180, v[172:175] offset:256
	ds_write_b128 v180, v[176:179] offset:384
	v_cvt_pk_bf16_f32 v64, v220, v224
	v_cvt_pk_bf16_f32 v164, v221, v225
	v_cvt_pk_bf16_f32 v172, v222, v226
	v_cvt_pk_bf16_f32 v176, v223, v227
	v_cvt_pk_bf16_f32 v65, v228, v232
	v_cvt_pk_bf16_f32 v165, v229, v233
	v_cvt_pk_bf16_f32 v173, v230, v234
	v_cvt_pk_bf16_f32 v177, v231, v235
	v_cvt_pk_bf16_f32 v66, v236, v240
	v_cvt_pk_bf16_f32 v166, v237, v241
	v_cvt_pk_bf16_f32 v174, v238, v242
	v_cvt_pk_bf16_f32 v178, v239, v243
	v_cvt_pk_bf16_f32 v67, v244, v248
	v_cvt_pk_bf16_f32 v167, v245, v249
	v_cvt_pk_bf16_f32 v175, v246, v250
	v_cvt_pk_bf16_f32 v179, v247, v251
	ds_write_b128 v181, v[64:67] offset:0
	ds_write_b128 v181, v[164:167] offset:128
	ds_write_b128 v181, v[172:175] offset:256
	ds_write_b128 v181, v[176:179] offset:384
	v_mad_u32_u24 v169, v69, s78, v128
	s_lshl_b32 s28, s78, 3
	s_waitcnt lgkmcnt(0)
	ds_read_b128 v[184:187], v182 offset:0
	ds_read_b128 v[188:191], v200 offset:1024
	ds_read_b128 v[192:195], v202 offset:2048
	ds_read_b128 v[196:199], v203 offset:3072
	ds_read_b128 v[204:207], v182 offset:4096
	ds_read_b128 v[208:211], v200 offset:5120
	ds_read_b128 v[212:215], v202 offset:6144
	ds_read_b128 v[216:219], v203 offset:7168
	s_waitcnt lgkmcnt(7)
	global_store_dwordx4 v169, v[184:187], s[76:77]
	s_add_u32 s76, s76, s28
	s_addc_u32 s77, s77, 0
	s_waitcnt lgkmcnt(6)
	global_store_dwordx4 v169, v[188:191], s[76:77]
	s_add_u32 s76, s76, s28
	s_addc_u32 s77, s77, 0
	s_waitcnt lgkmcnt(5)
	global_store_dwordx4 v169, v[192:195], s[76:77]
	s_add_u32 s76, s76, s28
	s_addc_u32 s77, s77, 0
	s_waitcnt lgkmcnt(4)
	global_store_dwordx4 v169, v[196:199], s[76:77]
	s_add_u32 s76, s76, s28
	s_addc_u32 s77, s77, 0
	s_waitcnt lgkmcnt(3)
	global_store_dwordx4 v169, v[204:207], s[76:77]
	s_add_u32 s76, s76, s28
	s_addc_u32 s77, s77, 0
	s_waitcnt lgkmcnt(2)
	global_store_dwordx4 v169, v[208:211], s[76:77]
	s_add_u32 s76, s76, s28
	s_addc_u32 s77, s77, 0
	s_waitcnt lgkmcnt(1)
	global_store_dwordx4 v169, v[212:215], s[76:77]
	s_add_u32 s76, s76, s28
	s_addc_u32 s77, s77, 0
	s_waitcnt lgkmcnt(0)
	global_store_dwordx4 v169, v[216:219], s[76:77]
	s_branch .Lp0_pe_b
.Lp0_px_b:
	v_cvt_pk_bf16_f32 v184, v184, v185
	v_cvt_pk_bf16_f32 v185, v186, v187
	v_cvt_pk_bf16_f32 v186, v188, v189
	v_cvt_pk_bf16_f32 v187, v190, v191
	global_store_dwordx4 v171, v[184:187], s[76:77] offset:0
	v_cvt_pk_bf16_f32 v192, v192, v193
	v_cvt_pk_bf16_f32 v193, v194, v195
	v_cvt_pk_bf16_f32 v194, v196, v197
	v_cvt_pk_bf16_f32 v195, v198, v199
	global_store_dwordx4 v171, v[192:195], s[76:77] offset:1024
	v_cvt_pk_bf16_f32 v204, v204, v205
	v_cvt_pk_bf16_f32 v205, v206, v207
	v_cvt_pk_bf16_f32 v206, v208, v209
	v_cvt_pk_bf16_f32 v207, v210, v211
	global_store_dwordx4 v171, v[204:207], s[76:77] offset:2048
	v_cvt_pk_bf16_f32 v212, v212, v213
	v_cvt_pk_bf16_f32 v213, v214, v215
	v_cvt_pk_bf16_f32 v214, v216, v217
	v_cvt_pk_bf16_f32 v215, v218, v219
	global_store_dwordx4 v171, v[212:215], s[76:77] offset:3072
	s_add_u32 s76, s76, 0x1000
	s_addc_u32 s77, s77, 0
	v_cvt_pk_bf16_f32 v220, v220, v221
	v_cvt_pk_bf16_f32 v221, v222, v223
	v_cvt_pk_bf16_f32 v222, v224, v225
	v_cvt_pk_bf16_f32 v223, v226, v227
	global_store_dwordx4 v171, v[220:223], s[76:77] offset:0
	v_cvt_pk_bf16_f32 v228, v228, v229
	v_cvt_pk_bf16_f32 v229, v230, v231
	v_cvt_pk_bf16_f32 v230, v232, v233
	v_cvt_pk_bf16_f32 v231, v234, v235
	global_store_dwordx4 v171, v[228:231], s[76:77] offset:1024
	v_cvt_pk_bf16_f32 v236, v236, v237
	v_cvt_pk_bf16_f32 v237, v238, v239
	v_cvt_pk_bf16_f32 v238, v240, v241
	v_cvt_pk_bf16_f32 v239, v242, v243
	global_store_dwordx4 v171, v[236:239], s[76:77] offset:2048
	v_cvt_pk_bf16_f32 v244, v244, v245
	v_cvt_pk_bf16_f32 v245, v246, v247
	v_cvt_pk_bf16_f32 v246, v248, v249
	v_cvt_pk_bf16_f32 v247, v250, v251
	global_store_dwordx4 v171, v[244:247], s[76:77] offset:3072
.Lp0_pe_b:
	s_cmp_lt_u32 s60, 24128
	s_cbranch_scc1 .Lp0_loop

; __device__ __forceinline__ unsigned pk2(float lo, float hi) { return f2bf(lo) | (f2bf(hi) << 16); }
; __global__ void __launch_bounds__(512, 2) fwd_megakernel(Args a) {
;     ...
;         for (int it = gw; it < I1 + I2 + I3 + I4 + I5; it += NGW) {
;             int r = it;
;             if (r < I1) { const int kb = r / 320, nb = r % 320; transpose_item(w_in_ab, 10240, 64 * kb, 32 * nb, WT1, 2048, 32 * nb, scr, lane); continue; } r -= I1;
;             if (r < I2) { const int kb = r / 64, nb = r % 64; transpose_item(w_out_ab, 2048, 64 * kb, 32 * nb, WT2, 3072, 32 * nb, scr, lane); continue; } r -= I2;
;             if (r < I3) { const int kb = r / 256, nb = r % 256; const int n0 = 32 * nb, part = n0 >> 11, chn = n0 & 2047;
;                 const int type = (part == 0 || part == 3) ? 1 : 0, bj = (part >= 2) ? 1 : 0;
;                 const int drow = 256 * (2 * (chn >> 7) + type) + 128 * bj + (chn & 127);
;                 transpose_item(w_in_c, 8192, 64 * kb, n0, WT3, 2048, drow, scr, lane); continue; } r -= I3;
;             if (r < I4) { const int kb = r / 64, nb = r % 64; transpose_item(w_out_c, 2048, 64 * kb, 32 * nb, WT4, 2048, 32 * nb, scr, lane); continue; } r -= I4;
;             { const int gi = r >> 5, rr = r & 31, kb = rr >> 3, nb = rr & 7; transpose_item(pool_w + (size_t)gi * 65536, 256, 64 * kb, 32 * nb, WT5, 256, gi * 256 + 32 * nb, scr, lane); }
;         }
;         for (size_t i = gt; i < (size_t)MT * DM / 8; i += (size_t)NGT * 4) {
;             f32x4 v0[4], v1[4];
; #pragma unroll
;             for (int u = 0; u < 4; ++u) { const size_t ii = i + (size_t)u * NGT; if (ii < (size_t)MT * DM / 8) { const size_t e = ii * 8; const float* src = e < (size_t)MP * DM ? x_prompt + e : x_sample + (e - (size_t)MP * DM);
;                 v0[u] = *(const f32x4*)src; v1[u] = *(const f32x4*)(src + 4); } }
; #pragma unroll
;             for (int u = 0; u < 4; ++u) { const size_t ii = i + (size_t)u * NGT; if (ii < (size_t)MT * DM / 8) { const size_t e = ii * 8;
;                 u32x4 o; o.x = pk2(v0[u][0], v0[u][1]); o.y = pk2(v0[u][2], v0[u][3]); o.z = pk2(v1[u][0], v1[u][1]); o.w = pk2(v1[u][2], v1[u][3]);
;                 *(u32x4*)(XB + e) = o; } } }
.LBB0_22:
	v_readlane_b32 s0, v255, 13
	s_nop 1
	v_lshl_add_u32 v176, s0, 9, v168
	v_readlane_b32 s0, v255, 9
	v_readlane_b32 s1, v255, 10
	s_lshl_b32 s0, s0, 9
	v_writelane_b32 v255, s0, 58
	s_nop 1
	v_writelane_b32 v255, s1, 59
	s_mov_b32 s0, 0x600000
	v_cmp_gt_u32_e32 vcc, s0, v176
	s_and_saveexec_b64 s[12:13], vcc
	s_branch .LBB0_37
